# P1 K-loop: loop edge rotated - LDS operand reads issued right after each barrier, scalar bookkeeping (pointer bumps, last-iteration test, m0/DMA setup) moved behind them
# speedup vs baseline: 1.0052x; 1.0012x over previous
.LBB0_327:
	s_ashr_i32 s23, s22, 31
	s_lshl_b64 s[24:25], s[22:23], 19
	s_add_u32 s24, s72, s24
	s_addc_u32 s25, s73, s25
	s_and_b64 s[26:27], s[6:7], exec
	s_cselect_b32 s23, s25, s47
	s_cselect_b32 s56, s24, s46
	s_ashr_i32 s21, s20, 31
	s_lshl_b64 s[26:27], s[20:21], 19
	s_add_u32 s26, s0, s26
	s_addc_u32 s27, s1, s27
	s_and_b64 s[48:49], s[6:7], exec
	s_cselect_b32 s57, s27, s31
	s_cselect_b32 s58, s26, s30
	s_lshl_b32 s21, s28, 8
	v_add_u32_e32 v6, s21, v227
	s_add_u32 s28, s46, 0x3ff80
	v_ashrrev_i32_e32 v7, 31, v6
	s_addc_u32 s29, s47, 0
	v_lshl_add_u64 v[214:215], v[6:7], 4, s[16:17]
	s_add_u32 s59, s30, 0
	v_mov_b32_e32 v6, 0
	s_addc_u32 s60, s31, 0
	s_mov_b32 s61, -2
	v_mov_b32_e32 v7, v6
	v_mov_b32_e32 v8, v6
	v_mov_b32_e32 v9, v6
	v_mov_b32_e32 v14, v6
	v_mov_b32_e32 v15, v6
	v_mov_b32_e32 v16, v6
	v_mov_b32_e32 v17, v6
	v_mov_b32_e32 v22, v6
	v_mov_b32_e32 v23, v6
	v_mov_b32_e32 v24, v6
	v_mov_b32_e32 v25, v6
	v_mov_b32_e32 v30, v6
	v_mov_b32_e32 v31, v6
	v_mov_b32_e32 v32, v6
	v_mov_b32_e32 v33, v6
	v_mov_b32_e32 v38, v6
	v_mov_b32_e32 v39, v6
	v_mov_b32_e32 v40, v6
	v_mov_b32_e32 v41, v6
	v_mov_b32_e32 v46, v6
	v_mov_b32_e32 v47, v6
	v_mov_b32_e32 v48, v6
	v_mov_b32_e32 v49, v6
	v_mov_b32_e32 v54, v6
	v_mov_b32_e32 v55, v6
	v_mov_b32_e32 v56, v6
	v_mov_b32_e32 v57, v6
	v_mov_b32_e32 v62, v6
	v_mov_b32_e32 v63, v6
	v_mov_b32_e32 v64, v6
	v_mov_b32_e32 v65, v6
	v_mov_b32_e32 v10, v6
	v_mov_b32_e32 v11, v6
	v_mov_b32_e32 v12, v6
	v_mov_b32_e32 v13, v6
	v_mov_b32_e32 v18, v6
	v_mov_b32_e32 v19, v6
	v_mov_b32_e32 v20, v6
	v_mov_b32_e32 v21, v6
	v_mov_b32_e32 v26, v6
	v_mov_b32_e32 v27, v6
	v_mov_b32_e32 v28, v6
	v_mov_b32_e32 v29, v6
	v_mov_b32_e32 v34, v6
	v_mov_b32_e32 v35, v6
	v_mov_b32_e32 v36, v6
	v_mov_b32_e32 v37, v6
	v_mov_b32_e32 v42, v6
	v_mov_b32_e32 v43, v6
	v_mov_b32_e32 v44, v6
	v_mov_b32_e32 v45, v6
	v_mov_b32_e32 v50, v6
	v_mov_b32_e32 v51, v6
	v_mov_b32_e32 v52, v6
	v_mov_b32_e32 v53, v6
	v_mov_b32_e32 v58, v6
	v_mov_b32_e32 v59, v6
	v_mov_b32_e32 v60, v6
	v_mov_b32_e32 v61, v6
	v_mov_b32_e32 v66, v6
	v_mov_b32_e32 v67, v6
	v_mov_b32_e32 v68, v6
	v_mov_b32_e32 v69, v6
	v_mov_b32_e32 v70, v6
	v_mov_b32_e32 v71, v6
	v_mov_b32_e32 v72, v6
	v_mov_b32_e32 v73, v6
	v_mov_b32_e32 v78, v6
	v_mov_b32_e32 v79, v6
	v_mov_b32_e32 v80, v6
	v_mov_b32_e32 v81, v6
	v_mov_b32_e32 v86, v6
	v_mov_b32_e32 v87, v6
	v_mov_b32_e32 v88, v6
	v_mov_b32_e32 v89, v6
	v_mov_b32_e32 v94, v6
	v_mov_b32_e32 v95, v6
	v_mov_b32_e32 v96, v6
	v_mov_b32_e32 v97, v6
	v_mov_b32_e32 v102, v6
	v_mov_b32_e32 v103, v6
	v_mov_b32_e32 v104, v6
	v_mov_b32_e32 v105, v6
	v_mov_b32_e32 v110, v6
	v_mov_b32_e32 v111, v6
	v_mov_b32_e32 v112, v6
	v_mov_b32_e32 v113, v6
	v_mov_b32_e32 v118, v6
	v_mov_b32_e32 v119, v6
	v_mov_b32_e32 v120, v6
	v_mov_b32_e32 v121, v6
	v_mov_b32_e32 v126, v6
	v_mov_b32_e32 v127, v6
	v_mov_b32_e32 v128, v6
	v_mov_b32_e32 v129, v6
	v_mov_b32_e32 v74, v6
	v_mov_b32_e32 v75, v6
	v_mov_b32_e32 v76, v6
	v_mov_b32_e32 v77, v6
	v_mov_b32_e32 v82, v6
	v_mov_b32_e32 v83, v6
	v_mov_b32_e32 v84, v6
	v_mov_b32_e32 v85, v6
	v_mov_b32_e32 v90, v6
	v_mov_b32_e32 v91, v6
	v_mov_b32_e32 v92, v6
	v_mov_b32_e32 v93, v6
	v_mov_b32_e32 v98, v6
	v_mov_b32_e32 v99, v6
	v_mov_b32_e32 v100, v6
	v_mov_b32_e32 v101, v6
	v_mov_b32_e32 v106, v6
	v_mov_b32_e32 v107, v6
	v_mov_b32_e32 v108, v6
	v_mov_b32_e32 v109, v6
	v_mov_b32_e32 v114, v6
	v_mov_b32_e32 v115, v6
	v_mov_b32_e32 v116, v6
	v_mov_b32_e32 v117, v6
	v_mov_b32_e32 v122, v6
	v_mov_b32_e32 v123, v6
	v_mov_b32_e32 v124, v6
	v_mov_b32_e32 v125, v6
	v_mov_b32_e32 v130, v6
	v_mov_b32_e32 v131, v6
	v_mov_b32_e32 v132, v6
	v_mov_b32_e32 v133, v6
	s_branch .LBB0_330

.LBB0_329:
	s_waitcnt lgkmcnt(0)
	s_barrier
	s_setprio 1
	s_waitcnt lgkmcnt(0)
	v_mfma_f32_16x16x32_bf16 v[66:69], v[150:153], v[190:193], v[66:69]
	v_mfma_f32_16x16x32_bf16 v[58:61], v[158:161], v[190:193], v[58:61]
	v_mfma_f32_16x16x32_bf16 v[50:53], v[150:153], v[182:185], v[50:53]
	v_mfma_f32_16x16x32_bf16 v[42:45], v[158:161], v[182:185], v[42:45]
	v_mfma_f32_16x16x32_bf16 v[34:37], v[150:153], v[174:177], v[34:37]
	v_mfma_f32_16x16x32_bf16 v[26:29], v[158:161], v[174:177], v[26:29]
	v_mfma_f32_16x16x32_bf16 v[18:21], v[150:153], v[166:169], v[18:21]
	v_mfma_f32_16x16x32_bf16 v[10:13], v[158:161], v[166:169], v[10:13]
	v_mfma_f32_16x16x32_bf16 v[66:69], v[154:157], v[194:197], v[66:69]
	v_mfma_f32_16x16x32_bf16 v[58:61], v[162:165], v[194:197], v[58:61]
	v_mfma_f32_16x16x32_bf16 v[50:53], v[154:157], v[186:189], v[50:53]
	v_mfma_f32_16x16x32_bf16 v[42:45], v[162:165], v[186:189], v[42:45]
	v_mfma_f32_16x16x32_bf16 v[34:37], v[154:157], v[178:181], v[34:37]
	v_mfma_f32_16x16x32_bf16 v[26:29], v[162:165], v[178:181], v[26:29]
	v_mfma_f32_16x16x32_bf16 v[18:21], v[154:157], v[170:173], v[18:21]
	v_mfma_f32_16x16x32_bf16 v[10:13], v[162:165], v[170:173], v[10:13]
	s_setprio 0
	s_setprio 1
	v_mfma_f32_16x16x32_bf16 v[62:65], v[134:137], v[190:193], v[62:65]
	v_mfma_f32_16x16x32_bf16 v[54:57], v[142:145], v[190:193], v[54:57]
	v_mfma_f32_16x16x32_bf16 v[46:49], v[134:137], v[182:185], v[46:49]
	v_mfma_f32_16x16x32_bf16 v[38:41], v[142:145], v[182:185], v[38:41]
	v_mfma_f32_16x16x32_bf16 v[30:33], v[134:137], v[174:177], v[30:33]
	v_mfma_f32_16x16x32_bf16 v[22:25], v[142:145], v[174:177], v[22:25]
	v_mfma_f32_16x16x32_bf16 v[14:17], v[134:137], v[166:169], v[14:17]
	v_mfma_f32_16x16x32_bf16 v[6:9], v[142:145], v[166:169], v[6:9]
	v_mfma_f32_16x16x32_bf16 v[62:65], v[138:141], v[194:197], v[62:65]
	v_mfma_f32_16x16x32_bf16 v[54:57], v[146:149], v[194:197], v[54:57]
	v_mfma_f32_16x16x32_bf16 v[46:49], v[138:141], v[186:189], v[46:49]
	v_mfma_f32_16x16x32_bf16 v[38:41], v[146:149], v[186:189], v[38:41]
	v_mfma_f32_16x16x32_bf16 v[30:33], v[138:141], v[178:181], v[30:33]
	v_mfma_f32_16x16x32_bf16 v[22:25], v[146:149], v[178:181], v[22:25]
	v_mfma_f32_16x16x32_bf16 v[14:17], v[138:141], v[170:173], v[14:17]
	v_mfma_f32_16x16x32_bf16 v[6:9], v[146:149], v[170:173], v[6:9]
	s_setprio 0
	s_barrier
	s_add_i32 s61, s61, 2
	s_cmp_gt_u32 s61, 13
	s_cbranch_scc1 .Lkr1_exit
.LBB0_330:
	v_add_u32_e32 v146, s53, v225
	v_add_u32_e32 v162, s54, v225
	ds_read_b128 v[134:137], v146
	ds_read_b128 v[138:141], v146 offset:1024
	ds_read_b128 v[142:145], v146 offset:2048
	ds_read_b128 v[146:149], v146 offset:3072
	ds_read_b128 v[150:153], v162
	ds_read_b128 v[154:157], v162 offset:1024
	ds_read_b128 v[158:161], v162 offset:2048
	ds_read_b128 v[162:165], v162 offset:3072
	ds_read_b128 v[166:169], v229
	ds_read_b128 v[170:173], v229 offset:1024
	ds_read_b128 v[174:177], v229 offset:2048
	ds_read_b128 v[178:181], v229 offset:3072
	ds_read_b128 v[182:185], v229 offset:4096
	ds_read_b128 v[186:189], v229 offset:5120
	ds_read_b128 v[190:193], v229 offset:6144
	ds_read_b128 v[194:197], v229 offset:7168
	s_add_u32 s28, s28, 0x100
	s_addc_u32 s29, s29, 0
	s_add_u32 s59, s59, 0x100
	s_addc_u32 s60, s60, 0
	s_cmp_eq_u32 s61, 12
	s_cselect_b64 s[30:31], -1, 0
	s_cbranch_scc0 .LBB0_332
	global_load_dwordx4 v[2:5], v[214:215], off
.LBB0_332:
	s_add_u32 s48, s28, 0xfffc0080
	s_addc_u32 s49, s29, -1
	s_and_b64 s[46:47], s[30:31], exec
	s_cselect_b32 s49, s23, s49
	s_cselect_b32 s48, s56, s48
	s_cselect_b32 s47, s57, s60
	s_cselect_b32 s46, s58, s59
	s_add_i32 m0, s40, 0xc000
	s_nop 0
	global_load_lds_dwordx4 v206, s[28:29]
	s_add_i32 m0, s40, 0xe000
	s_nop 0
	global_load_lds_dwordx4 v208, s[28:29]
	s_waitcnt vmcnt(8)
	s_waitcnt lgkmcnt(0)
	s_barrier
	s_setprio 1
	s_waitcnt lgkmcnt(0)
	v_mfma_f32_16x16x32_bf16 v[130:133], v[134:137], v[166:169], v[130:133]
	v_mfma_f32_16x16x32_bf16 v[122:125], v[142:145], v[166:169], v[122:125]
	v_mfma_f32_16x16x32_bf16 v[114:117], v[134:137], v[174:177], v[114:117]
	v_mfma_f32_16x16x32_bf16 v[106:109], v[142:145], v[174:177], v[106:109]
	v_mfma_f32_16x16x32_bf16 v[98:101], v[134:137], v[182:185], v[98:101]
	v_mfma_f32_16x16x32_bf16 v[90:93], v[142:145], v[182:185], v[90:93]
	v_mfma_f32_16x16x32_bf16 v[82:85], v[134:137], v[190:193], v[82:85]
	v_mfma_f32_16x16x32_bf16 v[74:77], v[142:145], v[190:193], v[74:77]
	v_mfma_f32_16x16x32_bf16 v[130:133], v[138:141], v[170:173], v[130:133]
	v_mfma_f32_16x16x32_bf16 v[122:125], v[146:149], v[170:173], v[122:125]
	v_mfma_f32_16x16x32_bf16 v[114:117], v[138:141], v[178:181], v[114:117]
	v_mfma_f32_16x16x32_bf16 v[106:109], v[146:149], v[178:181], v[106:109]
	v_mfma_f32_16x16x32_bf16 v[98:101], v[138:141], v[186:189], v[98:101]
	v_mfma_f32_16x16x32_bf16 v[90:93], v[146:149], v[186:189], v[90:93]
	v_mfma_f32_16x16x32_bf16 v[82:85], v[138:141], v[194:197], v[82:85]
	v_mfma_f32_16x16x32_bf16 v[74:77], v[146:149], v[194:197], v[74:77]
	s_setprio 0
	s_setprio 1
	v_mfma_f32_16x16x32_bf16 v[126:129], v[150:153], v[166:169], v[126:129]
	v_mfma_f32_16x16x32_bf16 v[118:121], v[158:161], v[166:169], v[118:121]
	v_mfma_f32_16x16x32_bf16 v[110:113], v[150:153], v[174:177], v[110:113]
	v_mfma_f32_16x16x32_bf16 v[102:105], v[158:161], v[174:177], v[102:105]
	v_mfma_f32_16x16x32_bf16 v[94:97], v[150:153], v[182:185], v[94:97]
	v_mfma_f32_16x16x32_bf16 v[86:89], v[158:161], v[182:185], v[86:89]
	v_mfma_f32_16x16x32_bf16 v[78:81], v[150:153], v[190:193], v[78:81]
	v_mfma_f32_16x16x32_bf16 v[70:73], v[158:161], v[190:193], v[70:73]
	v_mfma_f32_16x16x32_bf16 v[126:129], v[154:157], v[170:173], v[126:129]
	v_mfma_f32_16x16x32_bf16 v[118:121], v[162:165], v[170:173], v[118:121]
	v_mfma_f32_16x16x32_bf16 v[110:113], v[154:157], v[178:181], v[110:113]
	v_mfma_f32_16x16x32_bf16 v[102:105], v[162:165], v[178:181], v[102:105]
	v_mfma_f32_16x16x32_bf16 v[94:97], v[154:157], v[186:189], v[94:97]
	v_mfma_f32_16x16x32_bf16 v[86:89], v[162:165], v[186:189], v[86:89]
	v_mfma_f32_16x16x32_bf16 v[78:81], v[154:157], v[194:197], v[78:81]
	v_mfma_f32_16x16x32_bf16 v[70:73], v[162:165], v[194:197], v[70:73]
	s_setprio 0
	s_barrier
	ds_read_b128 v[166:169], v229 offset:16384
	ds_read_b128 v[170:173], v229 offset:17408
	ds_read_b128 v[174:177], v229 offset:18432
	ds_read_b128 v[178:181], v229 offset:19456
	ds_read_b128 v[182:185], v229 offset:20480
	ds_read_b128 v[186:189], v229 offset:21504
	ds_read_b128 v[190:193], v229 offset:22528
	ds_read_b128 v[194:197], v229 offset:23552
	s_add_i32 s62, s53, s12
	s_add_u32 s98, s46, s10
	s_addc_u32 s99, s47, s11
	s_mov_b32 m0, s62
	s_nop 0
	global_load_lds_dwordx4 v202, s[46:47]
	s_add_i32 m0, s62, 0x2000
	s_add_u32 s62, s46, 0x40000
	s_addc_u32 s63, s47, 0
	s_add_i32 s64, s54, s12
	global_load_lds_dwordx4 v198, s[46:47]
	s_mov_b32 m0, s64
	s_add_u32 s100, s48, s10
	s_addc_u32 s101, s49, s11
	global_load_lds_dwordx4 v202, s[62:63]
	s_add_i32 m0, s64, 0x2000
	s_nop 0
	global_load_lds_dwordx4 v198, s[62:63]
	s_mov_b32 m0, s40
	s_nop 0
	global_load_lds_dwordx4 v204, s[48:49]
	s_mov_b32 m0, s41
	s_nop 0
	global_load_lds_dwordx4 v200, s[48:49]
	s_waitcnt vmcnt(8)
	s_waitcnt lgkmcnt(0)
	s_barrier
	s_setprio 1
	s_waitcnt lgkmcnt(0)
	v_mfma_f32_16x16x32_bf16 v[66:69], v[134:137], v[166:169], v[66:69]
	v_mfma_f32_16x16x32_bf16 v[58:61], v[142:145], v[166:169], v[58:61]
	v_mfma_f32_16x16x32_bf16 v[50:53], v[134:137], v[174:177], v[50:53]
	v_mfma_f32_16x16x32_bf16 v[42:45], v[142:145], v[174:177], v[42:45]
	v_mfma_f32_16x16x32_bf16 v[34:37], v[134:137], v[182:185], v[34:37]
	v_mfma_f32_16x16x32_bf16 v[26:29], v[142:145], v[182:185], v[26:29]
	v_mfma_f32_16x16x32_bf16 v[18:21], v[134:137], v[190:193], v[18:21]
	v_mfma_f32_16x16x32_bf16 v[10:13], v[142:145], v[190:193], v[10:13]
	v_mfma_f32_16x16x32_bf16 v[66:69], v[138:141], v[170:173], v[66:69]
	v_mfma_f32_16x16x32_bf16 v[58:61], v[146:149], v[170:173], v[58:61]
	v_mfma_f32_16x16x32_bf16 v[50:53], v[138:141], v[178:181], v[50:53]
	v_mfma_f32_16x16x32_bf16 v[42:45], v[146:149], v[178:181], v[42:45]
	v_mfma_f32_16x16x32_bf16 v[34:37], v[138:141], v[186:189], v[34:37]
	v_mfma_f32_16x16x32_bf16 v[26:29], v[146:149], v[186:189], v[26:29]
	v_mfma_f32_16x16x32_bf16 v[18:21], v[138:141], v[194:197], v[18:21]
	v_mfma_f32_16x16x32_bf16 v[10:13], v[146:149], v[194:197], v[10:13]
	s_setprio 0
	s_setprio 1
	v_mfma_f32_16x16x32_bf16 v[62:65], v[150:153], v[166:169], v[62:65]
	v_mfma_f32_16x16x32_bf16 v[54:57], v[158:161], v[166:169], v[54:57]
	v_mfma_f32_16x16x32_bf16 v[46:49], v[150:153], v[174:177], v[46:49]
	v_mfma_f32_16x16x32_bf16 v[38:41], v[158:161], v[174:177], v[38:41]
	v_mfma_f32_16x16x32_bf16 v[30:33], v[150:153], v[182:185], v[30:33]
	v_mfma_f32_16x16x32_bf16 v[22:25], v[158:161], v[182:185], v[22:25]
	v_mfma_f32_16x16x32_bf16 v[14:17], v[150:153], v[190:193], v[14:17]
	v_mfma_f32_16x16x32_bf16 v[6:9], v[158:161], v[190:193], v[6:9]
	v_mfma_f32_16x16x32_bf16 v[62:65], v[154:157], v[170:173], v[62:65]
	v_mfma_f32_16x16x32_bf16 v[54:57], v[162:165], v[170:173], v[54:57]
	v_mfma_f32_16x16x32_bf16 v[46:49], v[154:157], v[178:181], v[46:49]
	v_mfma_f32_16x16x32_bf16 v[38:41], v[162:165], v[178:181], v[38:41]
	v_mfma_f32_16x16x32_bf16 v[30:33], v[154:157], v[186:189], v[30:33]
	v_mfma_f32_16x16x32_bf16 v[22:25], v[162:165], v[186:189], v[22:25]
	v_mfma_f32_16x16x32_bf16 v[14:17], v[154:157], v[194:197], v[14:17]
	v_mfma_f32_16x16x32_bf16 v[6:9], v[162:165], v[194:197], v[6:9]
	s_setprio 0
	s_barrier
	ds_read_b128 v[166:169], v229 offset:32768
	ds_read_b128 v[170:173], v229 offset:33792
	ds_read_b128 v[174:177], v229 offset:34816
	ds_read_b128 v[178:181], v229 offset:35840
	ds_read_b128 v[182:185], v229 offset:36864
	ds_read_b128 v[186:189], v229 offset:37888
	ds_read_b128 v[190:193], v229 offset:38912
	ds_read_b128 v[194:197], v229 offset:39936
	v_add_u32_e32 v134, 0x18000, v225
	v_add_u32_e32 v146, 0x1c000, v225
	ds_read_b128 v[150:153], v134
	ds_read_b128 v[154:157], v134 offset:1024
	ds_read_b128 v[158:161], v134 offset:2048
	ds_read_b128 v[162:165], v134 offset:3072
	ds_read_b128 v[134:137], v146
	ds_read_b128 v[138:141], v146 offset:1024
	ds_read_b128 v[142:145], v146 offset:2048
	ds_read_b128 v[146:149], v146 offset:3072
	s_add_i32 s62, 0, 0x18000
	s_add_i32 s63, 0, 0x1c000
	s_add_u32 s48, s48, 0x40000
	s_addc_u32 s49, s49, 0
	s_mov_b32 m0, s42
	s_nop 0
	global_load_lds_dwordx4 v204, s[48:49]
	s_mov_b32 m0, s43
	s_nop 0
	global_load_lds_dwordx4 v200, s[48:49]
	s_waitcnt vmcnt(8)
	s_waitcnt lgkmcnt(0)
	s_barrier
	s_setprio 1
	s_waitcnt lgkmcnt(0)
	v_mfma_f32_16x16x32_bf16 v[130:133], v[150:153], v[166:169], v[130:133]
	v_mfma_f32_16x16x32_bf16 v[122:125], v[158:161], v[166:169], v[122:125]
	v_mfma_f32_16x16x32_bf16 v[114:117], v[150:153], v[174:177], v[114:117]
	v_mfma_f32_16x16x32_bf16 v[106:109], v[158:161], v[174:177], v[106:109]
	v_mfma_f32_16x16x32_bf16 v[98:101], v[150:153], v[182:185], v[98:101]
	v_mfma_f32_16x16x32_bf16 v[90:93], v[158:161], v[182:185], v[90:93]
	v_mfma_f32_16x16x32_bf16 v[82:85], v[150:153], v[190:193], v[82:85]
	v_mfma_f32_16x16x32_bf16 v[74:77], v[158:161], v[190:193], v[74:77]
	v_mfma_f32_16x16x32_bf16 v[130:133], v[154:157], v[170:173], v[130:133]
	v_mfma_f32_16x16x32_bf16 v[122:125], v[162:165], v[170:173], v[122:125]
	v_mfma_f32_16x16x32_bf16 v[114:117], v[154:157], v[178:181], v[114:117]
	v_mfma_f32_16x16x32_bf16 v[106:109], v[162:165], v[178:181], v[106:109]
	v_mfma_f32_16x16x32_bf16 v[98:101], v[154:157], v[186:189], v[98:101]
	v_mfma_f32_16x16x32_bf16 v[90:93], v[162:165], v[186:189], v[90:93]
	v_mfma_f32_16x16x32_bf16 v[82:85], v[154:157], v[194:197], v[82:85]
	v_mfma_f32_16x16x32_bf16 v[74:77], v[162:165], v[194:197], v[74:77]
	s_setprio 0
	s_setprio 1
	v_mfma_f32_16x16x32_bf16 v[126:129], v[134:137], v[166:169], v[126:129]
	v_mfma_f32_16x16x32_bf16 v[118:121], v[142:145], v[166:169], v[118:121]
	v_mfma_f32_16x16x32_bf16 v[110:113], v[134:137], v[174:177], v[110:113]
	v_mfma_f32_16x16x32_bf16 v[102:105], v[142:145], v[174:177], v[102:105]
	v_mfma_f32_16x16x32_bf16 v[94:97], v[134:137], v[182:185], v[94:97]
	v_mfma_f32_16x16x32_bf16 v[86:89], v[142:145], v[182:185], v[86:89]
	v_mfma_f32_16x16x32_bf16 v[78:81], v[134:137], v[190:193], v[78:81]
	v_mfma_f32_16x16x32_bf16 v[70:73], v[142:145], v[190:193], v[70:73]
	v_mfma_f32_16x16x32_bf16 v[126:129], v[138:141], v[170:173], v[126:129]
	v_mfma_f32_16x16x32_bf16 v[118:121], v[146:149], v[170:173], v[118:121]
	v_mfma_f32_16x16x32_bf16 v[110:113], v[138:141], v[178:181], v[110:113]
	v_mfma_f32_16x16x32_bf16 v[102:105], v[146:149], v[178:181], v[102:105]
	v_mfma_f32_16x16x32_bf16 v[94:97], v[138:141], v[186:189], v[94:97]
	v_mfma_f32_16x16x32_bf16 v[86:89], v[146:149], v[186:189], v[86:89]
	v_mfma_f32_16x16x32_bf16 v[78:81], v[138:141], v[194:197], v[78:81]
	v_mfma_f32_16x16x32_bf16 v[70:73], v[146:149], v[194:197], v[70:73]
	s_setprio 0
	s_barrier
	ds_read_b128 v[190:193], v229 offset:49152
	ds_read_b128 v[194:197], v229 offset:50176
	ds_read_b128 v[182:185], v229 offset:51200
	ds_read_b128 v[186:189], v229 offset:52224
	ds_read_b128 v[174:177], v229 offset:53248
	ds_read_b128 v[178:181], v229 offset:54272
	ds_read_b128 v[166:169], v229 offset:55296
	ds_read_b128 v[170:173], v229 offset:56320
	s_add_i32 s48, s62, s12
	s_mov_b32 m0, s48
	s_nop 0
	global_load_lds_dwordx4 v202, s[98:99]
	s_add_i32 m0, s48, 0x2000
	s_add_u32 s46, s46, 0x40080
	s_addc_u32 s47, s47, 0
	s_add_i32 s48, s63, s12
	global_load_lds_dwordx4 v198, s[98:99]
	s_mov_b32 m0, s48
	s_andn2_b64 vcc, exec, s[30:31]
	global_load_lds_dwordx4 v202, s[46:47]
	s_add_i32 m0, s48, 0x2000
	s_nop 0
	global_load_lds_dwordx4 v198, s[46:47]
	s_mov_b32 m0, s51
	s_nop 0
	global_load_lds_dwordx4 v204, s[100:101]
	s_mov_b32 m0, s52
	s_nop 0
	global_load_lds_dwordx4 v200, s[100:101]
	s_waitcnt vmcnt(8)
	s_cbranch_vccnz .LBB0_329
	s_and_saveexec_b64 s[30:31], s[4:5]
	s_cbranch_execz .LBB0_328
	v_mov_b32_e32 v232, v3
	v_mov_b32_e32 v233, v4
	v_mov_b32_e32 v234, v2
	v_mov_b32_e32 v235, v5
	v_pk_add_f32 v[232:233], v[232:233], v[234:235]
	s_nop 0
	v_add_f32_e32 v226, v232, v233
	v_fmamk_f32 v226, v226, 0x3a800000, v230
	ds_write_b32 v228, v226
	s_branch .LBB0_328
.Lkr1_exit:
	s_add_u32 s28, s28, 0x100
	s_addc_u32 s29, s29, 0
	s_add_u32 s59, s59, 0x100
	s_addc_u32 s60, s60, 0
